# static slot-0 wave priority also during the mixers-phase-A compute items (not the page streaming)
# baseline (speedup 1.0000x reference)
.LBB0_332:
	s_cmp_eq_u32 s101, 3
	s_cbranch_scc1 .Lma_fin
	s_getreg_b32 s100, hwreg(HW_REG_HW_ID, 0, 4)
	s_cmp_lg_u32 s100, 0
	s_cbranch_scc1 .Lprio_done_s3
	s_setprio 1

.LBB0_490:
	s_cmp_eq_u32 s101, 2
	s_cbranch_scc0 .Lma_seam
	v_writelane_b32 v255, s7, 40
	v_writelane_b32 v255, s10, 41
	v_writelane_b32 v255, s11, 42
	v_writelane_b32 v255, s12, 43
	v_writelane_b32 v255, s13, 44
	v_writelane_b32 v255, s16, 45
	v_writelane_b32 v255, s17, 46
	v_writelane_b32 v255, s19, 47
	v_writelane_b32 v255, s20, 48
	v_writelane_b32 v255, s21, 49
	v_writelane_b32 v255, s35, 50
	v_writelane_b32 v255, s36, 51
	v_writelane_b32 v255, s40, 52
	v_writelane_b32 v255, s42, 53
	v_mov_b32_e32 v182, v2
	v_mov_b32_e32 v183, v3
	v_mov_b32_e32 v184, v4
	v_mov_b32_e32 v185, v109
	v_mov_b32_e32 v186, v123
	v_mov_b32_e32 v187, v125
	v_mov_b32_e32 v188, v127
	v_mov_b32_e32 v202, v129
	v_mov_b32_e32 v203, v131
	v_mov_b32_e32 v204, v133
	v_mov_b32_e32 v205, v135
	v_mov_b32_e32 v206, v137
	v_mov_b32_e32 v207, v139
	v_mov_b32_e32 v208, v141
	s_mov_b32 s101, 3
	s_setprio 0
	s_branch .Lma_s1
